# phase-9 SUMSQ loops: per-row sum of squares via v_dot2c_f32_bf16 (f32 accumulate) instead of unpack+pk_fma (50->16 VALU per k-step)
# speedup vs baseline: 1.1103x; 1.0036x over previous
.LBB0_69:
	s_add_i32 s3, s0, 1
	s_bitcmp1_b32 s3, 0
	s_cselect_b32 s1, 0x6000, 0
	v_or_b32_e32 v248, s1, v186
	v_add_u32_e32 v237, s1, v205
	v_add_u32_e32 v244, v248, v202
	v_add_u32_e32 v218, v237, v202
	ds_read_b128 v[238:241], v244 offset:16384
	ds_read_b128 v[244:247], v244 offset:18432
	ds_read_b128 v[206:209], v218
	ds_read_b128 v[210:213], v218 offset:2048
	ds_read_b128 v[214:217], v218 offset:4096
	ds_read_b128 v[218:221], v218 offset:6144
	v_mfma_f32_32x32x16_bf16 v[112:127], v[136:139], v[148:151], v[112:127]
	v_mfma_f32_32x32x16_bf16 v[96:111], v[132:135], v[148:151], v[96:111]
	v_mfma_f32_32x32x16_bf16 v[80:95], v[136:139], v[144:147], v[80:95]
	v_mfma_f32_32x32x16_bf16 v[64:79], v[132:135], v[144:147], v[64:79]
	v_mfma_f32_32x32x16_bf16 v[48:63], v[136:139], v[140:143], v[48:63]
	v_mfma_f32_32x32x16_bf16 v[32:47], v[132:135], v[140:143], v[32:47]
	v_mfma_f32_32x32x16_bf16 v[16:31], v[136:139], v[128:131], v[16:31]
	v_add_u32_e32 v136, v237, v204
	v_mfma_f32_32x32x16_bf16 v[0:15], v[132:135], v[128:131], v[0:15]
	v_add_u32_e32 v132, v248, v204
	ds_read_b128 v[148:151], v136
	ds_read_b128 v[144:147], v136 offset:2048
	ds_read_b128 v[140:143], v136 offset:4096
	ds_read_b128 v[128:131], v136 offset:6144
	ds_read_b128 v[136:139], v132 offset:16384
	ds_read_b128 v[132:135], v132 offset:18432
	s_waitcnt lgkmcnt(9)
	v_mfma_f32_32x32x16_bf16 v[112:127], v[238:241], v[206:209], v[112:127]
	v_mfma_f32_32x32x16_bf16 v[96:111], v[244:247], v[206:209], v[96:111]
	s_waitcnt lgkmcnt(8)
	v_mfma_f32_32x32x16_bf16 v[80:95], v[238:241], v[210:213], v[80:95]
	v_mfma_f32_32x32x16_bf16 v[64:79], v[244:247], v[210:213], v[64:79]
	s_waitcnt lgkmcnt(7)
	v_mfma_f32_32x32x16_bf16 v[48:63], v[238:241], v[214:217], v[48:63]
	v_mfma_f32_32x32x16_bf16 v[32:47], v[244:247], v[214:217], v[32:47]
	s_waitcnt lgkmcnt(6)
	v_mfma_f32_32x32x16_bf16 v[16:31], v[238:241], v[218:221], v[16:31]
	v_mfma_f32_32x32x16_bf16 v[0:15], v[244:247], v[218:221], v[0:15]
	s_waitcnt vmcnt(5)
	v_dot2c_f32_bf16_e32 v197, v152, v152
	v_dot2c_f32_bf16_e32 v197, v153, v153
	v_dot2c_f32_bf16_e32 v197, v154, v154
	v_dot2c_f32_bf16_e32 v197, v155, v155
	s_waitcnt vmcnt(4)
	v_dot2c_f32_bf16_e32 v196, v156, v156
	v_dot2c_f32_bf16_e32 v196, v157, v157
	v_dot2c_f32_bf16_e32 v196, v158, v158
	v_dot2c_f32_bf16_e32 v196, v159, v159
	s_bitcmp1_b32 s0, 0
	s_cselect_b32 s1, 0x6000, 0
	v_add_u32_e32 v212, s1, v203
	s_waitcnt vmcnt(1)
	ds_write_b128 v212, v[168:171] offset:16384
	v_dot2c_f32_bf16_e32 v199, v160, v160
	v_dot2c_f32_bf16_e32 v199, v161, v161
	v_dot2c_f32_bf16_e32 v199, v162, v162
	v_dot2c_f32_bf16_e32 v199, v163, v163
	v_dot2c_f32_bf16_e32 v198, v164, v164
	v_dot2c_f32_bf16_e32 v198, v165, v165
	v_dot2c_f32_bf16_e32 v198, v166, v166
	v_dot2c_f32_bf16_e32 v198, v167, v167
	s_waitcnt vmcnt(0)
	ds_write_b128 v212, v[172:175] offset:20480
	s_min_u32 s0, s0, 12
	s_lshl_b32 s66, s0, 6
	v_lshl_add_u64 v[168:169], v[176:177], 0, s[66:67]
	s_add_i32 s0, s66, 0xc0
	s_mov_b32 s1, s67
	ds_write_b128 v212, v[152:155]
	global_load_dwordx4 v[152:155], v[168:169], off offset:192
	v_lshl_add_u64 v[168:169], v[180:181], 0, s[0:1]
	ds_write_b128 v212, v[156:159] offset:4096
	global_load_dwordx4 v[156:159], v[168:169], off
	v_lshl_add_u64 v[168:169], v[182:183], 0, s[0:1]
	ds_write_b128 v212, v[160:163] offset:8192
	global_load_dwordx4 v[160:163], v[168:169], off
	v_lshl_add_u64 v[168:169], v[192:193], 0, s[0:1]
	ds_write_b128 v212, v[164:167] offset:12288
	global_load_dwordx4 v[164:167], v[168:169], off
	v_lshl_add_u64 v[168:169], v[178:179], 0, s[66:67]
	v_lshl_add_u64 v[172:173], v[194:195], 0, s[0:1]
	global_load_dwordx4 v[168:171], v[168:169], off offset:192
	s_cmp_eq_u32 s3, 14
	global_load_dwordx4 v[172:175], v[172:173], off
	s_mov_b32 s0, s3
	s_waitcnt lgkmcnt(0)
	s_barrier
	s_cbranch_scc0 .LBB0_69
	s_waitcnt vmcnt(0)
	v_add_u32_e32 v172, v186, v202
	v_add_u32_e32 v164, v205, v202
	ds_read_b128 v[168:171], v172 offset:40960
	ds_read_b128 v[172:175], v172 offset:43008
	ds_read_b128 v[152:155], v164 offset:24576
	ds_read_b128 v[156:159], v164 offset:26624
	ds_read_b128 v[160:163], v164 offset:28672
	ds_read_b128 v[164:167], v164 offset:30720
	v_mfma_f32_32x32x16_bf16 v[112:127], v[136:139], v[148:151], v[112:127]
	v_mfma_f32_32x32x16_bf16 v[96:111], v[132:135], v[148:151], v[96:111]
	v_add_u32_e32 v148, v186, v204
	v_mfma_f32_32x32x16_bf16 v[80:95], v[136:139], v[144:147], v[80:95]
	v_mfma_f32_32x32x16_bf16 v[64:79], v[132:135], v[144:147], v[64:79]
	v_mfma_f32_32x32x16_bf16 v[48:63], v[136:139], v[140:143], v[48:63]
	v_mfma_f32_32x32x16_bf16 v[32:47], v[132:135], v[140:143], v[32:47]
	v_add_u32_e32 v140, v205, v204
	v_mfma_f32_32x32x16_bf16 v[16:31], v[136:139], v[128:131], v[16:31]
	v_mfma_f32_32x32x16_bf16 v[0:15], v[132:135], v[128:131], v[0:15]
	ds_read_b128 v[128:131], v140 offset:24576
	ds_read_b128 v[132:135], v140 offset:26624
	ds_read_b128 v[136:139], v140 offset:28672
	ds_read_b128 v[140:143], v140 offset:30720
	ds_read_b128 v[144:147], v148 offset:40960
	ds_read_b128 v[148:151], v148 offset:43008
	s_waitcnt lgkmcnt(9)
	v_mfma_f32_32x32x16_bf16 v[112:127], v[168:171], v[152:155], v[112:127]
	v_mfma_f32_32x32x16_bf16 v[96:111], v[172:175], v[152:155], v[96:111]
	s_waitcnt lgkmcnt(8)
	v_mfma_f32_32x32x16_bf16 v[80:95], v[168:171], v[156:159], v[80:95]
	v_mfma_f32_32x32x16_bf16 v[64:79], v[172:175], v[156:159], v[64:79]
	s_waitcnt lgkmcnt(7)
	v_mfma_f32_32x32x16_bf16 v[48:63], v[168:171], v[160:163], v[48:63]
	v_mfma_f32_32x32x16_bf16 v[32:47], v[172:175], v[160:163], v[32:47]
	s_waitcnt lgkmcnt(6)
	v_mfma_f32_32x32x16_bf16 v[16:31], v[168:171], v[164:167], v[16:31]
	v_mfma_f32_32x32x16_bf16 v[0:15], v[172:175], v[164:167], v[0:15]
	v_cmp_lt_i32_e32 vcc, v233, v227
	s_waitcnt lgkmcnt(1)
	v_mfma_f32_32x32x16_bf16 v[112:127], v[144:147], v[128:131], v[112:127]
	s_waitcnt lgkmcnt(0)
	s_barrier
	v_mfma_f32_32x32x16_bf16 v[96:111], v[148:151], v[128:131], v[96:111]
	v_cndmask_b32_e32 v128, v226, v233, vcc
	v_lshlrev_b32_e32 v130, 2, v128
	ds_bpermute_b32 v129, v130, v197
	ds_bpermute_b32 v128, v130, v196
	ds_bpermute_b32 v131, v130, v199
	ds_bpermute_b32 v130, v130, v198
	v_cmp_lt_i32_e32 vcc, v232, v227
	v_mfma_f32_32x32x16_bf16 v[80:95], v[144:147], v[132:135], v[80:95]
	v_mfma_f32_32x32x16_bf16 v[64:79], v[148:151], v[132:135], v[64:79]
	s_waitcnt lgkmcnt(2)
	v_add_f32_e64 v132, v196, v128
	v_add_f32_e64 v133, v197, v129
	s_waitcnt lgkmcnt(0)
	v_add_f32_e64 v128, v198, v130
	v_add_f32_e64 v129, v199, v131
	v_cndmask_b32_e32 v130, v226, v232, vcc
	v_lshlrev_b32_e32 v130, 2, v130
	ds_bpermute_b32 v135, v130, v133
	ds_bpermute_b32 v134, v130, v132
	ds_bpermute_b32 v131, v130, v129
	v_mfma_f32_32x32x16_bf16 v[48:63], v[144:147], v[136:139], v[48:63]
	ds_bpermute_b32 v130, v130, v128
	v_cmp_eq_u32_e32 vcc, 0, v201
	v_mfma_f32_32x32x16_bf16 v[32:47], v[148:151], v[136:139], v[32:47]
	v_mfma_f32_32x32x16_bf16 v[16:31], v[144:147], v[140:143], v[16:31]
	v_mfma_f32_32x32x16_bf16 v[0:15], v[148:151], v[140:143], v[0:15]
	s_and_saveexec_b64 s[0:1], vcc
	s_cbranch_execz .LBB0_72
	s_mov_b32 s10, 0x358637bd
	s_waitcnt lgkmcnt(2)
	v_pk_add_f32 v[132:133], v[132:133], v[134:135]
	v_mov_b64_e32 v[134:135], s[10:11]
	s_mov_b32 s26, 0x3b000000
	v_pk_fma_f32 v[132:133], v[132:133], s[26:27], v[134:135] op_sel_hi:[1,0,0]
	s_waitcnt lgkmcnt(0)
	v_pk_add_f32 v[128:129], v[128:129], v[130:131]
	v_mul_f32_e32 v136, 0x4b800000, v133
	v_cmp_gt_f32_e32 vcc, s80, v133
	v_cmp_gt_f32_e64 s[10:11], s80, v132
	v_pk_fma_f32 v[128:129], v[128:129], s[26:27], v[134:135] op_sel_hi:[1,0,0]
	v_cndmask_b32_e32 v133, v133, v136, vcc
	v_mul_f32_e32 v136, 0x4b800000, v132
	v_rsq_f32_e32 v133, v133
	v_cndmask_b32_e64 v132, v132, v136, s[10:11]
	v_rsq_f32_e32 v132, v132
	v_mul_f32_e32 v130, 0x4b800000, v129
	v_mul_f32_e32 v137, 0x45800000, v133
	v_cndmask_b32_e32 v133, v133, v137, vcc
	v_mul_f32_e32 v137, 0x45800000, v132
	v_cmp_gt_f32_e32 vcc, s80, v129
	v_cndmask_b32_e64 v132, v132, v137, s[10:11]
	v_cmp_gt_f32_e64 s[10:11], s80, v128
	v_cndmask_b32_e32 v129, v129, v130, vcc
	v_mul_f32_e32 v130, 0x4b800000, v128
	v_rsq_f32_e32 v129, v129
	v_cndmask_b32_e64 v128, v128, v130, s[10:11]
	v_rsq_f32_e32 v128, v128
	v_lshlrev_b32_e32 v136, 2, v200
	v_mul_f32_e32 v130, 0x45800000, v129
	v_cndmask_b32_e32 v129, v129, v130, vcc
	v_mul_f32_e32 v130, 0x45800000, v128
	v_cndmask_b32_e64 v128, v128, v130, s[10:11]
	ds_write2st64_b32 v136, v133, v132 offset0:192 offset1:193
	ds_write2st64_b32 v136, v129, v128 offset0:194 offset1:195

.LBB0_75:
	s_add_i32 s3, s0, 1
	s_bitcmp1_b32 s3, 0
	s_cselect_b32 s1, 0x6000, 0
	v_add_u32_e32 v237, s1, v186
	v_or_b32_e32 v248, s1, v204
	v_add_u32_e32 v218, v237, v202
	v_add_u32_e32 v244, v248, v202
	ds_read_b128 v[206:209], v218
	ds_read_b128 v[210:213], v218 offset:2048
	ds_read_b128 v[214:217], v218 offset:4096
	ds_read_b128 v[218:221], v218 offset:6144
	ds_read_b128 v[238:241], v244 offset:16384
	ds_read_b128 v[244:247], v244 offset:18432
	v_mfma_f32_32x32x16_bf16 v[112:127], v[148:151], v[136:139], v[112:127]
	v_mfma_f32_32x32x16_bf16 v[96:111], v[148:151], v[132:135], v[96:111]
	v_mfma_f32_32x32x16_bf16 v[80:95], v[144:147], v[136:139], v[80:95]
	v_mfma_f32_32x32x16_bf16 v[64:79], v[144:147], v[132:135], v[64:79]
	v_mfma_f32_32x32x16_bf16 v[48:63], v[140:143], v[136:139], v[48:63]
	v_mfma_f32_32x32x16_bf16 v[32:47], v[140:143], v[132:135], v[32:47]
	v_mfma_f32_32x32x16_bf16 v[16:31], v[128:131], v[136:139], v[16:31]
	v_add_u32_e32 v136, v237, v205
	v_mfma_f32_32x32x16_bf16 v[0:15], v[128:131], v[132:135], v[0:15]
	v_add_u32_e32 v132, v248, v205
	ds_read_b128 v[148:151], v136
	ds_read_b128 v[144:147], v136 offset:2048
	ds_read_b128 v[140:143], v136 offset:4096
	ds_read_b128 v[128:131], v136 offset:6144
	ds_read_b128 v[136:139], v132 offset:16384
	ds_read_b128 v[132:135], v132 offset:18432
	s_waitcnt lgkmcnt(7)
	v_mfma_f32_32x32x16_bf16 v[112:127], v[206:209], v[238:241], v[112:127]
	s_waitcnt lgkmcnt(6)
	v_mfma_f32_32x32x16_bf16 v[96:111], v[206:209], v[244:247], v[96:111]
	v_mfma_f32_32x32x16_bf16 v[80:95], v[210:213], v[238:241], v[80:95]
	v_mfma_f32_32x32x16_bf16 v[64:79], v[210:213], v[244:247], v[64:79]
	v_mfma_f32_32x32x16_bf16 v[48:63], v[214:217], v[238:241], v[48:63]
	v_mfma_f32_32x32x16_bf16 v[32:47], v[214:217], v[244:247], v[32:47]
	v_mfma_f32_32x32x16_bf16 v[16:31], v[218:221], v[238:241], v[16:31]
	v_mfma_f32_32x32x16_bf16 v[0:15], v[218:221], v[244:247], v[0:15]
	s_waitcnt vmcnt(5)
	v_dot2c_f32_bf16_e32 v197, v152, v152
	v_dot2c_f32_bf16_e32 v197, v153, v153
	v_dot2c_f32_bf16_e32 v197, v154, v154
	v_dot2c_f32_bf16_e32 v197, v155, v155
	s_waitcnt vmcnt(4)
	v_dot2c_f32_bf16_e32 v196, v156, v156
	v_dot2c_f32_bf16_e32 v196, v157, v157
	v_dot2c_f32_bf16_e32 v196, v158, v158
	v_dot2c_f32_bf16_e32 v196, v159, v159
	s_bitcmp1_b32 s0, 0
	s_cselect_b32 s1, 0x6000, 0
	v_add_u32_e32 v212, s1, v203
	s_waitcnt vmcnt(1)
	ds_write_b128 v212, v[168:171] offset:16384
	v_dot2c_f32_bf16_e32 v199, v160, v160
	v_dot2c_f32_bf16_e32 v199, v161, v161
	v_dot2c_f32_bf16_e32 v199, v162, v162
	v_dot2c_f32_bf16_e32 v199, v163, v163
	v_dot2c_f32_bf16_e32 v198, v164, v164
	v_dot2c_f32_bf16_e32 v198, v165, v165
	v_dot2c_f32_bf16_e32 v198, v166, v166
	v_dot2c_f32_bf16_e32 v198, v167, v167
	s_waitcnt vmcnt(0)
	ds_write_b128 v212, v[172:175] offset:20480
	s_min_u32 s0, s0, 12
	s_lshl_b32 s66, s0, 6
	v_lshl_add_u64 v[168:169], v[176:177], 0, s[66:67]
	s_add_i32 s0, s66, 0xc0
	s_mov_b32 s1, s67
	ds_write_b128 v212, v[152:155]
	global_load_dwordx4 v[152:155], v[168:169], off offset:192
	v_lshl_add_u64 v[168:169], v[180:181], 0, s[0:1]
	ds_write_b128 v212, v[156:159] offset:4096
	global_load_dwordx4 v[156:159], v[168:169], off
	v_lshl_add_u64 v[168:169], v[182:183], 0, s[0:1]
	ds_write_b128 v212, v[160:163] offset:8192
	global_load_dwordx4 v[160:163], v[168:169], off
	v_lshl_add_u64 v[168:169], v[192:193], 0, s[0:1]
	ds_write_b128 v212, v[164:167] offset:12288
	global_load_dwordx4 v[164:167], v[168:169], off
	v_lshl_add_u64 v[168:169], v[178:179], 0, s[66:67]
	v_lshl_add_u64 v[172:173], v[194:195], 0, s[0:1]
	global_load_dwordx4 v[168:171], v[168:169], off offset:192
	s_cmp_eq_u32 s3, 14
	global_load_dwordx4 v[172:175], v[172:173], off
	s_mov_b32 s0, s3
	s_waitcnt lgkmcnt(0)
	s_barrier
	s_cbranch_scc0 .LBB0_75
	s_waitcnt vmcnt(2)
	v_add_u32_e32 v164, v186, v202
	ds_read_b128 v[152:155], v164 offset:24576
	ds_read_b128 v[156:159], v164 offset:26624
	ds_read_b128 v[160:163], v164 offset:28672
	ds_read_b128 v[164:167], v164 offset:30720
	s_waitcnt vmcnt(0)
	v_add_u32_e32 v172, v204, v202
	ds_read_b128 v[168:171], v172 offset:40960
	ds_read_b128 v[172:175], v172 offset:43008
	v_mfma_f32_32x32x16_bf16 v[112:127], v[148:151], v[136:139], v[112:127]
	v_mfma_f32_32x32x16_bf16 v[96:111], v[148:151], v[132:135], v[96:111]
	v_add_u32_e32 v148, v204, v205
	v_mfma_f32_32x32x16_bf16 v[80:95], v[144:147], v[136:139], v[80:95]
	v_mfma_f32_32x32x16_bf16 v[64:79], v[144:147], v[132:135], v[64:79]
	v_mfma_f32_32x32x16_bf16 v[48:63], v[140:143], v[136:139], v[48:63]
	v_mfma_f32_32x32x16_bf16 v[32:47], v[140:143], v[132:135], v[32:47]
	v_add_u32_e32 v140, v186, v205
	v_mfma_f32_32x32x16_bf16 v[16:31], v[128:131], v[136:139], v[16:31]
	v_mfma_f32_32x32x16_bf16 v[0:15], v[128:131], v[132:135], v[0:15]
	ds_read_b128 v[128:131], v140 offset:24576
	ds_read_b128 v[132:135], v140 offset:26624
	ds_read_b128 v[136:139], v140 offset:28672
	ds_read_b128 v[140:143], v140 offset:30720
	ds_read_b128 v[144:147], v148 offset:40960
	ds_read_b128 v[148:151], v148 offset:43008
	s_waitcnt lgkmcnt(7)
	v_mfma_f32_32x32x16_bf16 v[112:127], v[152:155], v[168:171], v[112:127]
	s_waitcnt lgkmcnt(6)
	v_mfma_f32_32x32x16_bf16 v[96:111], v[152:155], v[172:175], v[96:111]
	v_mfma_f32_32x32x16_bf16 v[80:95], v[156:159], v[168:171], v[80:95]
	v_mfma_f32_32x32x16_bf16 v[64:79], v[156:159], v[172:175], v[64:79]
	v_mfma_f32_32x32x16_bf16 v[48:63], v[160:163], v[168:171], v[48:63]
	v_mfma_f32_32x32x16_bf16 v[32:47], v[160:163], v[172:175], v[32:47]
	v_mfma_f32_32x32x16_bf16 v[16:31], v[164:167], v[168:171], v[16:31]
	v_mfma_f32_32x32x16_bf16 v[0:15], v[164:167], v[172:175], v[0:15]
	v_cmp_lt_i32_e32 vcc, v233, v227
	s_waitcnt lgkmcnt(1)
	v_mfma_f32_32x32x16_bf16 v[112:127], v[128:131], v[144:147], v[112:127]
	s_waitcnt lgkmcnt(0)
	s_barrier
	v_mfma_f32_32x32x16_bf16 v[96:111], v[128:131], v[148:151], v[96:111]
	v_cndmask_b32_e32 v128, v226, v233, vcc
	v_lshlrev_b32_e32 v130, 2, v128
	ds_bpermute_b32 v129, v130, v197
	ds_bpermute_b32 v128, v130, v196
	ds_bpermute_b32 v131, v130, v199
	ds_bpermute_b32 v130, v130, v198
	v_cmp_lt_i32_e32 vcc, v232, v227
	v_mfma_f32_32x32x16_bf16 v[80:95], v[132:135], v[144:147], v[80:95]
	v_mfma_f32_32x32x16_bf16 v[64:79], v[132:135], v[148:151], v[64:79]
	s_waitcnt lgkmcnt(2)
	v_add_f32_e64 v132, v196, v128
	v_add_f32_e64 v133, v197, v129
	s_waitcnt lgkmcnt(0)
	v_add_f32_e64 v128, v198, v130
	v_add_f32_e64 v129, v199, v131
	v_cndmask_b32_e32 v130, v226, v232, vcc
	v_lshlrev_b32_e32 v130, 2, v130
	ds_bpermute_b32 v135, v130, v133
	ds_bpermute_b32 v134, v130, v132
	ds_bpermute_b32 v131, v130, v129
	v_mfma_f32_32x32x16_bf16 v[48:63], v[136:139], v[144:147], v[48:63]
	ds_bpermute_b32 v130, v130, v128
	v_cmp_eq_u32_e32 vcc, 0, v201
	v_mfma_f32_32x32x16_bf16 v[32:47], v[136:139], v[148:151], v[32:47]
	v_mfma_f32_32x32x16_bf16 v[16:31], v[140:143], v[144:147], v[16:31]
	v_mfma_f32_32x32x16_bf16 v[0:15], v[140:143], v[148:151], v[0:15]
	s_and_saveexec_b64 s[0:1], vcc
	s_cbranch_execz .LBB0_78
	s_mov_b32 s10, 0x358637bd
	s_waitcnt lgkmcnt(2)
	v_pk_add_f32 v[132:133], v[132:133], v[134:135]
	v_mov_b64_e32 v[134:135], s[10:11]
	s_mov_b32 s26, 0x3b000000
	v_pk_fma_f32 v[132:133], v[132:133], s[26:27], v[134:135] op_sel_hi:[1,0,0]
	s_waitcnt lgkmcnt(0)
	v_pk_add_f32 v[128:129], v[128:129], v[130:131]
	v_mul_f32_e32 v136, 0x4b800000, v133
	v_cmp_gt_f32_e32 vcc, s80, v133
	v_cmp_gt_f32_e64 s[10:11], s80, v132
	v_pk_fma_f32 v[128:129], v[128:129], s[26:27], v[134:135] op_sel_hi:[1,0,0]
	v_cndmask_b32_e32 v133, v133, v136, vcc
	v_mul_f32_e32 v136, 0x4b800000, v132
	v_rsq_f32_e32 v133, v133
	v_cndmask_b32_e64 v132, v132, v136, s[10:11]
	v_rsq_f32_e32 v132, v132
	v_mul_f32_e32 v130, 0x4b800000, v129
	v_mul_f32_e32 v137, 0x45800000, v133
	v_cndmask_b32_e32 v133, v133, v137, vcc
	v_mul_f32_e32 v137, 0x45800000, v132
	v_cmp_gt_f32_e32 vcc, s80, v129
	v_cndmask_b32_e64 v132, v132, v137, s[10:11]
	v_cmp_gt_f32_e64 s[10:11], s80, v128
	v_cndmask_b32_e32 v129, v129, v130, vcc
	v_mul_f32_e32 v130, 0x4b800000, v128
	v_rsq_f32_e32 v129, v129
	v_cndmask_b32_e64 v128, v128, v130, s[10:11]
	v_rsq_f32_e32 v128, v128
	v_lshlrev_b32_e32 v136, 2, v200
	v_mul_f32_e32 v130, 0x45800000, v129
	v_cndmask_b32_e32 v129, v129, v130, vcc
	v_mul_f32_e32 v130, 0x45800000, v128
	v_cndmask_b32_e64 v128, v128, v130, s[10:11]
	ds_write2st64_b32 v136, v133, v132 offset0:192 offset1:193
	ds_write2st64_b32 v136, v129, v128 offset0:194 offset1:195

.LBB0_81:
	s_add_i32 s9, s0, 1
	s_bitcmp1_b32 s9, 0
	s_cselect_b32 s1, 0x6000, 0
	v_add_u32_e32 v218, s1, v186
	v_or_b32_e32 v219, s1, v204
	v_add_u32_e32 v220, v218, v202
	v_add_u32_e32 v221, v219, v202
	ds_read_b128 v[206:209], v220
	ds_read_b128 v[210:213], v220 offset:2048
	ds_read_b128 v[214:217], v220 offset:4096
	ds_read_b128 v[238:241], v220 offset:6144
	ds_read_b128 v[244:247], v221 offset:16384
	ds_read_b128 v[248:251], v221 offset:18432
	v_mfma_f32_32x32x16_bf16 v[112:127], v[148:151], v[136:139], v[112:127]
	v_mfma_f32_32x32x16_bf16 v[96:111], v[148:151], v[132:135], v[96:111]
	v_mfma_f32_32x32x16_bf16 v[80:95], v[144:147], v[136:139], v[80:95]
	v_mfma_f32_32x32x16_bf16 v[64:79], v[144:147], v[132:135], v[64:79]
	v_mfma_f32_32x32x16_bf16 v[48:63], v[140:143], v[136:139], v[48:63]
	v_mfma_f32_32x32x16_bf16 v[32:47], v[140:143], v[132:135], v[32:47]
	v_mfma_f32_32x32x16_bf16 v[16:31], v[128:131], v[136:139], v[16:31]
	v_add_u32_e32 v136, v218, v205
	v_mfma_f32_32x32x16_bf16 v[0:15], v[128:131], v[132:135], v[0:15]
	v_add_u32_e32 v132, v219, v205
	ds_read_b128 v[148:151], v136
	ds_read_b128 v[144:147], v136 offset:2048
	ds_read_b128 v[140:143], v136 offset:4096
	ds_read_b128 v[128:131], v136 offset:6144
	ds_read_b128 v[136:139], v132 offset:16384
	ds_read_b128 v[132:135], v132 offset:18432
	s_waitcnt lgkmcnt(7)
	v_mfma_f32_32x32x16_bf16 v[112:127], v[206:209], v[244:247], v[112:127]
	s_waitcnt lgkmcnt(6)
	v_mfma_f32_32x32x16_bf16 v[96:111], v[206:209], v[248:251], v[96:111]
	v_mfma_f32_32x32x16_bf16 v[80:95], v[210:213], v[244:247], v[80:95]
	v_mfma_f32_32x32x16_bf16 v[64:79], v[210:213], v[248:251], v[64:79]
	v_mfma_f32_32x32x16_bf16 v[48:63], v[214:217], v[244:247], v[48:63]
	v_mfma_f32_32x32x16_bf16 v[32:47], v[214:217], v[248:251], v[32:47]
	v_mfma_f32_32x32x16_bf16 v[16:31], v[238:241], v[244:247], v[16:31]
	v_mfma_f32_32x32x16_bf16 v[0:15], v[238:241], v[248:251], v[0:15]
	s_waitcnt vmcnt(5)
	v_dot2c_f32_bf16_e32 v197, v152, v152
	v_dot2c_f32_bf16_e32 v197, v153, v153
	v_dot2c_f32_bf16_e32 v197, v154, v154
	v_dot2c_f32_bf16_e32 v197, v155, v155
	s_waitcnt vmcnt(4)
	v_dot2c_f32_bf16_e32 v196, v156, v156
	v_dot2c_f32_bf16_e32 v196, v157, v157
	v_dot2c_f32_bf16_e32 v196, v158, v158
	v_dot2c_f32_bf16_e32 v196, v159, v159
	s_bitcmp1_b32 s0, 0
	s_cselect_b32 s1, 0x6000, 0
	v_add_u32_e32 v212, s1, v203
	s_waitcnt vmcnt(1)
	ds_write_b128 v212, v[168:171] offset:16384
	v_dot2c_f32_bf16_e32 v199, v160, v160
	v_dot2c_f32_bf16_e32 v199, v161, v161
	v_dot2c_f32_bf16_e32 v199, v162, v162
	v_dot2c_f32_bf16_e32 v199, v163, v163
	v_dot2c_f32_bf16_e32 v198, v164, v164
	v_dot2c_f32_bf16_e32 v198, v165, v165
	v_dot2c_f32_bf16_e32 v198, v166, v166
	v_dot2c_f32_bf16_e32 v198, v167, v167
	s_waitcnt vmcnt(0)
	ds_write_b128 v212, v[172:175] offset:20480
	s_min_u32 s0, s0, 12
	s_lshl_b32 s66, s0, 6
	v_lshl_add_u64 v[168:169], v[176:177], 0, s[66:67]
	s_add_i32 s0, s66, 0xc0
	s_mov_b32 s1, s67
	ds_write_b128 v212, v[152:155]
	global_load_dwordx4 v[152:155], v[168:169], off offset:192
	v_lshl_add_u64 v[168:169], v[180:181], 0, s[0:1]
	ds_write_b128 v212, v[156:159] offset:4096
	global_load_dwordx4 v[156:159], v[168:169], off
	v_lshl_add_u64 v[168:169], v[182:183], 0, s[0:1]
	ds_write_b128 v212, v[160:163] offset:8192
	global_load_dwordx4 v[160:163], v[168:169], off
	v_lshl_add_u64 v[168:169], v[192:193], 0, s[0:1]
	ds_write_b128 v212, v[164:167] offset:12288
	global_load_dwordx4 v[164:167], v[168:169], off
	v_lshl_add_u64 v[168:169], v[178:179], 0, s[66:67]
	v_lshl_add_u64 v[172:173], v[194:195], 0, s[0:1]
	global_load_dwordx4 v[168:171], v[168:169], off offset:192
	s_cmp_eq_u32 s9, 14
	global_load_dwordx4 v[172:175], v[172:173], off
	s_mov_b32 s0, s9
	s_waitcnt lgkmcnt(0)
	s_barrier
	s_cbranch_scc0 .LBB0_81
	s_waitcnt vmcnt(2)
	v_add_u32_e32 v164, v186, v202
	ds_read_b128 v[152:155], v164 offset:24576
	ds_read_b128 v[156:159], v164 offset:26624
	ds_read_b128 v[160:163], v164 offset:28672
	ds_read_b128 v[164:167], v164 offset:30720
	s_waitcnt vmcnt(0)
	v_add_u32_e32 v172, v204, v202
	ds_read_b128 v[168:171], v172 offset:40960
	ds_read_b128 v[172:175], v172 offset:43008
	v_mfma_f32_32x32x16_bf16 v[112:127], v[148:151], v[136:139], v[112:127]
	v_mfma_f32_32x32x16_bf16 v[96:111], v[148:151], v[132:135], v[96:111]
	v_add_u32_e32 v148, v204, v205
	v_mfma_f32_32x32x16_bf16 v[80:95], v[144:147], v[136:139], v[80:95]
	v_mfma_f32_32x32x16_bf16 v[64:79], v[144:147], v[132:135], v[64:79]
	v_mfma_f32_32x32x16_bf16 v[48:63], v[140:143], v[136:139], v[48:63]
	v_mfma_f32_32x32x16_bf16 v[32:47], v[140:143], v[132:135], v[32:47]
	v_add_u32_e32 v140, v186, v205
	v_mfma_f32_32x32x16_bf16 v[16:31], v[128:131], v[136:139], v[16:31]
	v_mfma_f32_32x32x16_bf16 v[0:15], v[128:131], v[132:135], v[0:15]
	ds_read_b128 v[128:131], v140 offset:24576
	ds_read_b128 v[132:135], v140 offset:26624
	ds_read_b128 v[136:139], v140 offset:28672
	ds_read_b128 v[140:143], v140 offset:30720
	ds_read_b128 v[144:147], v148 offset:40960
	ds_read_b128 v[148:151], v148 offset:43008
	s_waitcnt lgkmcnt(7)
	v_mfma_f32_32x32x16_bf16 v[112:127], v[152:155], v[168:171], v[112:127]
	s_waitcnt lgkmcnt(6)
	v_mfma_f32_32x32x16_bf16 v[96:111], v[152:155], v[172:175], v[96:111]
	v_mfma_f32_32x32x16_bf16 v[80:95], v[156:159], v[168:171], v[80:95]
	v_mfma_f32_32x32x16_bf16 v[64:79], v[156:159], v[172:175], v[64:79]
	v_mfma_f32_32x32x16_bf16 v[48:63], v[160:163], v[168:171], v[48:63]
	v_mfma_f32_32x32x16_bf16 v[32:47], v[160:163], v[172:175], v[32:47]
	v_mfma_f32_32x32x16_bf16 v[16:31], v[164:167], v[168:171], v[16:31]
	v_mfma_f32_32x32x16_bf16 v[0:15], v[164:167], v[172:175], v[0:15]
	v_cmp_lt_i32_e32 vcc, v233, v227
	s_waitcnt lgkmcnt(1)
	v_mfma_f32_32x32x16_bf16 v[112:127], v[128:131], v[144:147], v[112:127]
	s_waitcnt lgkmcnt(0)
	s_barrier
	v_mfma_f32_32x32x16_bf16 v[96:111], v[128:131], v[148:151], v[96:111]
	v_cndmask_b32_e32 v128, v226, v233, vcc
	v_lshlrev_b32_e32 v130, 2, v128
	ds_bpermute_b32 v129, v130, v197
	ds_bpermute_b32 v128, v130, v196
	ds_bpermute_b32 v131, v130, v199
	ds_bpermute_b32 v130, v130, v198
	v_cmp_lt_i32_e32 vcc, v232, v227
	v_mfma_f32_32x32x16_bf16 v[80:95], v[132:135], v[144:147], v[80:95]
	v_mfma_f32_32x32x16_bf16 v[64:79], v[132:135], v[148:151], v[64:79]
	s_waitcnt lgkmcnt(2)
	v_add_f32_e64 v132, v196, v128
	v_add_f32_e64 v133, v197, v129
	s_waitcnt lgkmcnt(0)
	v_add_f32_e64 v128, v198, v130
	v_add_f32_e64 v129, v199, v131
	v_cndmask_b32_e32 v130, v226, v232, vcc
	v_lshlrev_b32_e32 v130, 2, v130
	ds_bpermute_b32 v135, v130, v133
	ds_bpermute_b32 v134, v130, v132
	ds_bpermute_b32 v131, v130, v129
	v_mfma_f32_32x32x16_bf16 v[48:63], v[136:139], v[144:147], v[48:63]
	ds_bpermute_b32 v130, v130, v128
	v_cmp_eq_u32_e32 vcc, 0, v201
	v_mfma_f32_32x32x16_bf16 v[32:47], v[136:139], v[148:151], v[32:47]
	v_mfma_f32_32x32x16_bf16 v[16:31], v[140:143], v[144:147], v[16:31]
	v_mfma_f32_32x32x16_bf16 v[0:15], v[140:143], v[148:151], v[0:15]
	s_and_saveexec_b64 s[0:1], vcc
	s_cbranch_execz .LBB0_84
	s_mov_b32 s10, 0x358637bd
	s_waitcnt lgkmcnt(2)
	v_pk_add_f32 v[132:133], v[132:133], v[134:135]
	v_mov_b64_e32 v[134:135], s[10:11]
	s_mov_b32 s24, 0x3b000000
	v_pk_fma_f32 v[132:133], v[132:133], s[24:25], v[134:135] op_sel_hi:[1,0,0]
	s_waitcnt lgkmcnt(0)
	v_pk_add_f32 v[128:129], v[128:129], v[130:131]
	v_mul_f32_e32 v136, 0x4b800000, v133
	v_cmp_gt_f32_e32 vcc, s80, v133
	v_cmp_gt_f32_e64 s[10:11], s80, v132
	v_pk_fma_f32 v[128:129], v[128:129], s[24:25], v[134:135] op_sel_hi:[1,0,0]
	v_cndmask_b32_e32 v133, v133, v136, vcc
	v_mul_f32_e32 v136, 0x4b800000, v132
	v_rsq_f32_e32 v133, v133
	v_cndmask_b32_e64 v132, v132, v136, s[10:11]
	v_rsq_f32_e32 v132, v132
	v_mul_f32_e32 v130, 0x4b800000, v129
	v_mul_f32_e32 v137, 0x45800000, v133
	v_cndmask_b32_e32 v133, v133, v137, vcc
	v_mul_f32_e32 v137, 0x45800000, v132
	v_cmp_gt_f32_e32 vcc, s80, v129
	v_cndmask_b32_e64 v132, v132, v137, s[10:11]
	v_cmp_gt_f32_e64 s[10:11], s80, v128
	v_cndmask_b32_e32 v129, v129, v130, vcc
	v_mul_f32_e32 v130, 0x4b800000, v128
	v_rsq_f32_e32 v129, v129
	v_cndmask_b32_e64 v128, v128, v130, s[10:11]
	v_rsq_f32_e32 v128, v128
	v_lshlrev_b32_e32 v136, 2, v200
	v_mul_f32_e32 v130, 0x45800000, v129
	v_cndmask_b32_e32 v129, v129, v130, vcc
	v_mul_f32_e32 v130, 0x45800000, v128
	v_cndmask_b32_e64 v128, v128, v130, s[10:11]
	ds_write2st64_b32 v136, v133, v132 offset0:192 offset1:193
	ds_write2st64_b32 v136, v129, v128 offset0:194 offset1:195
